# the two side-phase norm loops (norm2 latents beside out-proj ctx tiles, norm1-next latents beside down-proj ctx tiles) also issue all 16 loads up front
# speedup vs baseline: 1.0201x; 1.0055x over previous
; __device__ __forceinline__ unsigned pk2(float lo, float hi) { f32x2_pk v = {lo, hi}; bf16x2_pk b = __builtin_convertvector(v, bf16x2_pk); return __builtin_bit_cast(unsigned, b); }
; __device__ __forceinline__ void norm_phase(const float* xl, const float* xc, const float* g, const float* shift, const float* scale, bf16_t* Z, int row_lo, int nrows, int gw, int ngw, int lane) {
;     for (int m = row_lo + gw; m < nrows; m += ngw) {
;         const float* xr = m < ML ? xl + (size_t)m * D : xc + (size_t)(m - ML) * D; const int mr = m < ML ? (m >> 11) : 16;
;         f32x4 v[4]; float ss = 0.f;
; #pragma unroll
;         for (int j = 0; j < 4; ++j) { v[j] = *(const f32x4*)(xr + 4 * lane + 256 * j); ss += (v[j].x * v[j].x + v[j].y * v[j].y) + (v[j].z * v[j].z + v[j].w * v[j].w); }
;         const float ri = rsqrtf(wave_sum(ss) * (1.0f / D) + 1e-6f);
; #pragma unroll
;         for (int j = 0; j < 4; ++j) { const int c = 4 * lane + 256 * j; const f32x4 gv = *(const f32x4*)(g + c), sh = *(const f32x4*)(shift + (size_t)mr * 6144 + c), sc = *(const f32x4*)(scale + (size_t)mr * 6144 + c);
;             const f32x4 o = v[j] * ri * gv * (sc + 1.0f) + sh; u32x2 w; w.x = pk2(o.x, o.y); w.y = pk2(o.z, o.w); *(u32x2*)(Z + (size_t)m * D + c) = w; }
;     }
; }
.LBB0_1653:
	s_addk_i32 s1, 0x600
	s_ashr_i32 s4, s1, 11
	global_load_dwordx4 v[64:67], v[24:25], off offset:-2048
	global_load_dwordx4 v[68:71], v[24:25], off offset:-1024
	global_load_dwordx4 v[72:75], v[24:25], off
	global_load_dwordx4 v[76:79], v[24:25], off offset:1024
	global_load_dwordx4 v[80:83], v[16:17], off
	v_mad_i64_i32 v[84:85], s[2:3], s4, v212, v[20:21]
	global_load_dwordx4 v[88:91], v[84:85], off
	v_mad_i64_i32 v[92:93], s[2:3], s4, v212, v[18:19]
	global_load_dwordx4 v[96:99], v[92:93], off
	global_load_dwordx4 v[100:103], v[16:17], off offset:1024
	global_load_dwordx4 v[104:107], v[92:93], off offset:1024
	global_load_dwordx4 v[108:111], v[84:85], off offset:1024
	global_load_dwordx4 v[112:115], v[16:17], off offset:2048
	global_load_dwordx4 v[116:119], v[92:93], off offset:2048
	global_load_dwordx4 v[120:123], v[84:85], off offset:2048
	global_load_dwordx4 v[124:127], v[16:17], off offset:3072
	global_load_dwordx4 v[128:131], v[92:93], off offset:3072
	global_load_dwordx4 v[132:135], v[84:85], off offset:3072
	s_cmpk_lt_i32 s1, 0x7a00
	s_waitcnt vmcnt(15)
	v_pk_mul_f32 v[0:1], v[66:67], v[66:67]
	v_pk_mul_f32 v[2:3], v[64:65], v[64:65]
	s_nop 0
	v_pk_mov_b32 v[4:5], v[2:3], v[0:1] op_sel:[1,0]
	v_mov_b32_e32 v3, v1
	v_pk_add_f32 v[28:29], v[4:5], v[2:3]
	s_waitcnt vmcnt(14)
	v_pk_mul_f32 v[0:1], v[70:71], v[70:71]
	v_pk_mul_f32 v[2:3], v[68:69], v[68:69]
	v_pk_add_f32 v[28:29], v[28:29], v[28:29] op_sel:[0,1] op_sel_hi:[1,0]
	v_pk_mov_b32 v[4:5], v[2:3], v[0:1] op_sel:[1,0]
	v_mov_b32_e32 v3, v1
	v_pk_add_f32 v[30:31], v[4:5], v[2:3]
	v_pk_add_f32 v[30:31], v[30:31], v[30:31] op_sel:[0,1] op_sel_hi:[1,0]
	v_lshl_add_u64 v[24:25], v[24:25], 0, s[60:61]
	s_waitcnt vmcnt(12)
	v_mul_f32_e32 v26, v76, v76
	v_mul_f32_e32 v37, v77, v77
	v_mov_b32_e32 v29, v26
	v_mov_b32_e32 v31, v37
	v_mul_f32_e32 v26, v73, v73
	v_mul_f32_e32 v38, v78, v78
	v_pk_add_f32 v[28:29], v[28:29], v[30:31]
	v_pk_fma_f32 v[30:31], v[72:73], v[72:73], v[26:27] op_sel_hi:[1,1,0]
	v_mul_f32_e32 v26, v75, v75
	v_mul_f32_e32 v40, v79, v79
	v_mov_b32_e32 v31, v38
	v_pk_fma_f32 v[38:39], v[74:75], v[74:75], v[26:27] op_sel_hi:[1,1,0]
	s_nop 0
	v_mov_b32_e32 v39, v40
	v_pk_add_f32 v[30:31], v[30:31], v[38:39]
	v_pk_add_f32 v[28:29], v[28:29], v[30:31]
	v_add_f32_e32 v26, v28, v29
	s_nop 1
	v_add_f32_dpp v26, v26, v26 quad_perm:[1,0,3,2] row_mask:0xf bank_mask:0xf
	s_nop 1
	v_add_f32_dpp v26, v26, v26 quad_perm:[2,3,0,1] row_mask:0xf bank_mask:0xf
	s_nop 1
	v_add_f32_dpp v26, v26, v26 row_half_mirror row_mask:0xf bank_mask:0xf
	s_nop 1
	v_add_f32_dpp v26, v26, v26 row_mirror row_mask:0xf bank_mask:0xf
	v_mov_b32_e32 v28, v26
	s_nop 1
	v_permlane16_swap_b32_e32 v26, v28
	v_add_f32_e32 v26, v26, v28
	v_mov_b32_e32 v28, v26
	s_nop 1
	v_permlane32_swap_b32_e32 v26, v28
	v_add_f32_e32 v26, v26, v28
	s_waitcnt lgkmcnt(0)
	v_fmamk_f32 v26, v26, 0x3a800000, v199
	v_cmp_gt_f32_e32 vcc, s64, v26
	v_mul_f32_e32 v28, 0x4b800000, v26
	s_nop 0
	v_cndmask_b32_e32 v26, v26, v28, vcc
	v_rsq_f32_e32 v26, v26
	s_nop 0
	v_mul_f32_e32 v28, 0x45800000, v26
	v_cndmask_b32_e32 v26, v26, v28, vcc
	v_pk_mul_f32 v[66:67], v[66:67], v[26:27] op_sel_hi:[1,0]
	v_pk_mul_f32 v[64:65], v[64:65], v[26:27] op_sel_hi:[1,0]
	v_pk_mul_f32 v[70:71], v[70:71], v[26:27] op_sel_hi:[1,0]
	v_pk_mul_f32 v[68:69], v[68:69], v[26:27] op_sel_hi:[1,0]
	v_pk_mul_f32 v[74:75], v[74:75], v[26:27] op_sel_hi:[1,0]
	v_pk_mul_f32 v[72:73], v[72:73], v[26:27] op_sel_hi:[1,0]
	v_pk_mul_f32 v[78:79], v[78:79], v[26:27] op_sel_hi:[1,0]
	v_pk_mul_f32 v[76:77], v[76:77], v[26:27] op_sel_hi:[1,0]
	s_waitcnt vmcnt(11)
	v_pk_mul_f32 v[64:65], v[80:81], v[64:65]
	v_pk_mul_f32 v[66:67], v[82:83], v[66:67]
	s_waitcnt vmcnt(10)
	v_pk_add_f32 v[80:81], v[90:91], 1.0 op_sel_hi:[1,0]
	v_pk_add_f32 v[82:83], v[88:89], 1.0 op_sel_hi:[1,0]
	s_waitcnt vmcnt(9)
	v_pk_fma_f32 v[66:67], v[80:81], v[66:67], v[98:99]
	v_pk_fma_f32 v[64:65], v[82:83], v[64:65], v[96:97]
	s_nop 0
	v_cvt_pk_bf16_f32 v64, v64, v65
	v_cvt_pk_bf16_f32 v65, v66, v67
	global_store_dwordx2 v[22:23], v[64:65], off
	s_nop 0
	s_waitcnt vmcnt(9)
	v_pk_mul_f32 v[68:69], v[100:101], v[68:69]
	v_pk_mul_f32 v[70:71], v[102:103], v[70:71]
	s_waitcnt vmcnt(7)
	v_pk_add_f32 v[100:101], v[110:111], 1.0 op_sel_hi:[1,0]
	v_pk_add_f32 v[102:103], v[108:109], 1.0 op_sel_hi:[1,0]
	v_pk_fma_f32 v[70:71], v[100:101], v[70:71], v[106:107]
	v_pk_fma_f32 v[68:69], v[102:103], v[68:69], v[104:105]
	s_nop 0
	v_cvt_pk_bf16_f32 v68, v68, v69
	v_cvt_pk_bf16_f32 v69, v70, v71
	global_store_dwordx2 v[22:23], v[68:69], off offset:512
	s_nop 0
	s_waitcnt vmcnt(7)
	v_pk_mul_f32 v[72:73], v[112:113], v[72:73]
	v_pk_mul_f32 v[74:75], v[114:115], v[74:75]
	s_waitcnt vmcnt(5)
	v_pk_add_f32 v[112:113], v[122:123], 1.0 op_sel_hi:[1,0]
	v_pk_add_f32 v[114:115], v[120:121], 1.0 op_sel_hi:[1,0]
	v_pk_fma_f32 v[74:75], v[112:113], v[74:75], v[118:119]
	v_pk_fma_f32 v[72:73], v[114:115], v[72:73], v[116:117]
	s_nop 0
	v_cvt_pk_bf16_f32 v72, v72, v73
	v_cvt_pk_bf16_f32 v73, v74, v75
	global_store_dwordx2 v[22:23], v[72:73], off offset:1024
	s_nop 0
	s_waitcnt vmcnt(5)
	v_pk_mul_f32 v[124:125], v[124:125], v[76:77]
	v_pk_mul_f32 v[126:127], v[126:127], v[78:79]
	s_waitcnt vmcnt(3)
	v_pk_add_f32 v[76:77], v[134:135], 1.0 op_sel_hi:[1,0]
	v_pk_add_f32 v[78:79], v[132:133], 1.0 op_sel_hi:[1,0]
	v_pk_fma_f32 v[126:127], v[126:127], v[76:77], v[130:131]
	v_pk_fma_f32 v[124:125], v[124:125], v[78:79], v[128:129]
	s_nop 0
	v_cvt_pk_bf16_f32 v124, v124, v125
	v_cvt_pk_bf16_f32 v125, v126, v127
	global_store_dwordx2 v[22:23], v[124:125], off offset:1536
	v_lshl_add_u64 v[22:23], v[22:23], 0, s[58:59]
	s_cbranch_scc1 .LBB0_1653

; __device__ __forceinline__ unsigned pk2(float lo, float hi) { f32x2_pk v = {lo, hi}; bf16x2_pk b = __builtin_convertvector(v, bf16x2_pk); return __builtin_bit_cast(unsigned, b); }
; __device__ __forceinline__ void norm_phase(const float* xl, const float* xc, const float* g, const float* shift, const float* scale, bf16_t* Z, int row_lo, int nrows, int gw, int ngw, int lane) {
;     for (int m = row_lo + gw; m < nrows; m += ngw) {
;         const float* xr = m < ML ? xl + (size_t)m * D : xc + (size_t)(m - ML) * D; const int mr = m < ML ? (m >> 11) : 16;
;         f32x4 v[4]; float ss = 0.f;
; #pragma unroll
;         for (int j = 0; j < 4; ++j) { v[j] = *(const f32x4*)(xr + 4 * lane + 256 * j); ss += (v[j].x * v[j].x + v[j].y * v[j].y) + (v[j].z * v[j].z + v[j].w * v[j].w); }
;         const float ri = rsqrtf(wave_sum(ss) * (1.0f / D) + 1e-6f);
; #pragma unroll
;         for (int j = 0; j < 4; ++j) { const int c = 4 * lane + 256 * j; const f32x4 gv = *(const f32x4*)(g + c), sh = *(const f32x4*)(shift + (size_t)mr * 6144 + c), sc = *(const f32x4*)(scale + (size_t)mr * 6144 + c);
;             const f32x4 o = v[j] * ri * gv * (sc + 1.0f) + sh; u32x2 w; w.x = pk2(o.x, o.y); w.y = pk2(o.z, o.w); *(u32x2*)(Z + (size_t)m * D + c) = w; }
;     }
; }
.LBB0_2005:
	s_addk_i32 s2, 0x600
	s_ashr_i32 s3, s2, 11
	global_load_dwordx4 v[64:67], v[26:27], off offset:-2048
	global_load_dwordx4 v[68:71], v[26:27], off offset:-1024
	global_load_dwordx4 v[72:75], v[26:27], off
	global_load_dwordx4 v[76:79], v[26:27], off offset:1024
	global_load_dwordx4 v[80:83], v[18:19], off
	v_mad_i64_i32 v[84:85], s[12:13], s3, v212, v[22:23]
	v_mad_i64_i32 v[86:87], s[12:13], s3, v212, v[20:21]
	global_load_dwordx4 v[88:91], v[86:87], off
	global_load_dwordx4 v[92:95], v[84:85], off
	global_load_dwordx4 v[96:99], v[18:19], off offset:1024
	global_load_dwordx4 v[100:103], v[86:87], off offset:1024
	global_load_dwordx4 v[104:107], v[84:85], off offset:1024
	global_load_dwordx4 v[108:111], v[18:19], off offset:2048
	global_load_dwordx4 v[112:115], v[86:87], off offset:2048
	global_load_dwordx4 v[116:119], v[84:85], off offset:2048
	global_load_dwordx4 v[120:123], v[18:19], off offset:3072
	global_load_dwordx4 v[124:127], v[86:87], off offset:3072
	global_load_dwordx4 v[128:131], v[84:85], off offset:3072
	s_cmpk_lt_i32 s2, 0x7a00
	s_waitcnt vmcnt(15)
	v_pk_mul_f32 v[0:1], v[66:67], v[66:67]
	v_pk_mul_f32 v[2:3], v[64:65], v[64:65]
	s_nop 0
	v_pk_mov_b32 v[4:5], v[2:3], v[0:1] op_sel:[1,0]
	v_mov_b32_e32 v3, v1
	v_pk_add_f32 v[30:31], v[4:5], v[2:3]
	s_waitcnt vmcnt(14)
	v_pk_mul_f32 v[0:1], v[70:71], v[70:71]
	v_pk_mul_f32 v[2:3], v[68:69], v[68:69]
	v_pk_add_f32 v[30:31], v[30:31], v[30:31] op_sel:[0,1] op_sel_hi:[1,0]
	v_pk_mov_b32 v[4:5], v[2:3], v[0:1] op_sel:[1,0]
	v_mov_b32_e32 v3, v1
	v_pk_add_f32 v[32:33], v[4:5], v[2:3]
	v_pk_add_f32 v[32:33], v[32:33], v[32:33] op_sel:[0,1] op_sel_hi:[1,0]
	v_lshl_add_u64 v[26:27], v[26:27], 0, s[60:61]
	s_waitcnt vmcnt(12)
	v_mul_f32_e32 v17, v76, v76
	v_mul_f32_e32 v28, v77, v77
	v_mov_b32_e32 v31, v17
	v_mov_b32_e32 v33, v28
	v_mul_f32_e32 v28, v73, v73
	v_pk_add_f32 v[30:31], v[30:31], v[32:33]
	v_pk_fma_f32 v[32:33], v[72:73], v[72:73], v[28:29] op_sel_hi:[1,1,0]
	v_mul_f32_e32 v28, v75, v75
	v_mul_f32_e32 v41, v78, v78
	v_mul_f32_e32 v44, v79, v79
	v_pk_fma_f32 v[42:43], v[74:75], v[74:75], v[28:29] op_sel_hi:[1,1,0]
	v_mov_b32_e32 v33, v41
	v_mov_b32_e32 v43, v44
	v_pk_add_f32 v[32:33], v[32:33], v[42:43]
	v_pk_add_f32 v[30:31], v[30:31], v[32:33]
	v_add_f32_e32 v17, v30, v31
	s_nop 1
	v_add_f32_dpp v17, v17, v17 quad_perm:[1,0,3,2] row_mask:0xf bank_mask:0xf
	s_nop 1
	v_add_f32_dpp v17, v17, v17 quad_perm:[2,3,0,1] row_mask:0xf bank_mask:0xf
	s_nop 1
	v_add_f32_dpp v17, v17, v17 row_half_mirror row_mask:0xf bank_mask:0xf
	s_nop 1
	v_add_f32_dpp v17, v17, v17 row_mirror row_mask:0xf bank_mask:0xf
	v_mov_b32_e32 v28, v17
	s_nop 1
	v_permlane16_swap_b32_e32 v17, v28
	v_add_f32_e32 v17, v17, v28
	v_mov_b32_e32 v28, v17
	s_nop 1
	v_permlane32_swap_b32_e32 v17, v28
	v_add_f32_e32 v17, v17, v28
	s_waitcnt lgkmcnt(0)
	v_fmamk_f32 v17, v17, 0x3a800000, v199
	v_cmp_gt_f32_e32 vcc, s64, v17
	v_mul_f32_e32 v28, 0x4b800000, v17
	s_nop 0
	v_cndmask_b32_e32 v17, v17, v28, vcc
	v_rsq_f32_e32 v17, v17
	s_nop 0
	v_mul_f32_e32 v28, 0x45800000, v17
	v_cndmask_b32_e32 v28, v17, v28, vcc
	v_pk_mul_f32 v[66:67], v[66:67], v[28:29] op_sel_hi:[1,0]
	v_pk_mul_f32 v[64:65], v[64:65], v[28:29] op_sel_hi:[1,0]
	v_pk_mul_f32 v[70:71], v[70:71], v[28:29] op_sel_hi:[1,0]
	v_pk_mul_f32 v[68:69], v[68:69], v[28:29] op_sel_hi:[1,0]
	v_pk_mul_f32 v[74:75], v[74:75], v[28:29] op_sel_hi:[1,0]
	v_pk_mul_f32 v[72:73], v[72:73], v[28:29] op_sel_hi:[1,0]
	v_pk_mul_f32 v[78:79], v[78:79], v[28:29] op_sel_hi:[1,0]
	v_pk_mul_f32 v[76:77], v[76:77], v[28:29] op_sel_hi:[1,0]
	s_waitcnt vmcnt(11)
	v_pk_mul_f32 v[64:65], v[80:81], v[64:65]
	v_pk_mul_f32 v[66:67], v[82:83], v[66:67]
	s_waitcnt vmcnt(9)
	v_pk_add_f32 v[80:81], v[94:95], 1.0 op_sel_hi:[1,0]
	v_pk_add_f32 v[82:83], v[92:93], 1.0 op_sel_hi:[1,0]
	v_pk_fma_f32 v[66:67], v[80:81], v[66:67], v[90:91]
	v_pk_fma_f32 v[64:65], v[82:83], v[64:65], v[88:89]
	s_nop 0
	v_cvt_pk_bf16_f32 v64, v64, v65
	v_cvt_pk_bf16_f32 v65, v66, v67
	global_store_dwordx2 v[24:25], v[64:65], off
	s_nop 0
	s_waitcnt vmcnt(9)
	v_pk_mul_f32 v[68:69], v[96:97], v[68:69]
	v_pk_mul_f32 v[70:71], v[98:99], v[70:71]
	s_waitcnt vmcnt(7)
	v_pk_add_f32 v[96:97], v[106:107], 1.0 op_sel_hi:[1,0]
	v_pk_add_f32 v[98:99], v[104:105], 1.0 op_sel_hi:[1,0]
	v_pk_fma_f32 v[70:71], v[96:97], v[70:71], v[102:103]
	v_pk_fma_f32 v[68:69], v[98:99], v[68:69], v[100:101]
	s_nop 0
	v_cvt_pk_bf16_f32 v68, v68, v69
	v_cvt_pk_bf16_f32 v69, v70, v71
	global_store_dwordx2 v[24:25], v[68:69], off offset:512
	s_nop 0
	s_waitcnt vmcnt(7)
	v_pk_mul_f32 v[72:73], v[108:109], v[72:73]
	v_pk_mul_f32 v[74:75], v[110:111], v[74:75]
	s_waitcnt vmcnt(5)
	v_pk_add_f32 v[108:109], v[118:119], 1.0 op_sel_hi:[1,0]
	v_pk_add_f32 v[110:111], v[116:117], 1.0 op_sel_hi:[1,0]
	v_pk_fma_f32 v[74:75], v[108:109], v[74:75], v[114:115]
	v_pk_fma_f32 v[72:73], v[110:111], v[72:73], v[112:113]
	s_nop 0
	v_cvt_pk_bf16_f32 v72, v72, v73
	v_cvt_pk_bf16_f32 v73, v74, v75
	global_store_dwordx2 v[24:25], v[72:73], off offset:1024
	s_nop 0
	s_waitcnt vmcnt(5)
	v_pk_mul_f32 v[120:121], v[120:121], v[76:77]
	v_pk_mul_f32 v[122:123], v[122:123], v[78:79]
	s_waitcnt vmcnt(3)
	v_pk_add_f32 v[76:77], v[130:131], 1.0 op_sel_hi:[1,0]
	v_pk_add_f32 v[78:79], v[128:129], 1.0 op_sel_hi:[1,0]
	v_pk_fma_f32 v[122:123], v[122:123], v[76:77], v[126:127]
	v_pk_fma_f32 v[120:121], v[120:121], v[78:79], v[124:125]
	s_nop 0
	v_cvt_pk_bf16_f32 v120, v120, v121
	v_cvt_pk_bf16_f32 v121, v122, v123
	global_store_dwordx2 v[24:25], v[120:121], off offset:1536
	v_lshl_add_u64 v[24:25], v[24:25], 0, s[58:59]
	s_cbranch_scc1 .LBB0_2005
